# early acquire: the grid barrier's L1 invalidate is issued at arrival (followers before the first poll, XCD leader right after the write-back) instead of after the release is observed
# speedup vs baseline: 1.0093x; 1.0021x over previous
.LBB0_25:
	s_or_b64 exec, exec, s[10:11]
	v_cvt_f32_u32_e32 v5, v3
	s_waitcnt vmcnt(0)
	v_readfirstlane_b32 s8, v4
	v_sub_u32_e32 v4, 0, v3
	v_rcp_iflag_f32_e32 v5, v5
	v_add_u32_e32 v6, s8, v2
	v_mul_f32_e32 v5, 0x4f7ffffe, v5
	v_cvt_u32_f32_e32 v5, v5
	v_mul_lo_u32 v2, v4, v5
	v_mul_hi_u32 v2, v5, v2
	v_add_u32_e32 v2, v5, v2
	v_mul_hi_u32 v2, v6, v2
	v_mul_lo_u32 v4, v2, v3
	v_sub_u32_e32 v4, v6, v4
	v_add_u32_e32 v5, 1, v2
	v_sub_u32_e32 v7, v4, v3
	v_cmp_ge_u32_e32 vcc, v4, v3
	s_nop 1
	v_cndmask_b32_e32 v2, v2, v5, vcc
	v_cndmask_b32_e32 v4, v4, v7, vcc
	v_add_u32_e32 v5, 1, v2
	v_cmp_ge_u32_e32 vcc, v4, v3
	v_add_u32_e32 v4, 1, v6
	s_nop 0
	v_cndmask_b32_e32 v2, v2, v5, vcc
	v_mul_lo_u32 v5, v3, v2
	v_add_u32_e32 v3, v5, v3
	v_cmp_ne_u32_e32 vcc, v4, v3
	s_and_saveexec_b64 s[8:9], vcc
	s_xor_b64 s[8:9], exec, s[8:9]
	s_cbranch_execz .LBB0_39
	s_waitcnt lgkmcnt(0)
	buffer_inv sc1
	v_mov_b32_e32 v1, 0x2000
	global_load_dword v1, v1, s[6:7] offset:1024 sc1
	s_add_u32 s12, s6, 0x2400
	s_addc_u32 s13, s7, 0
	s_waitcnt vmcnt(0)
	v_cmp_eq_u32_e32 vcc, v1, v2
	s_and_saveexec_b64 s[10:11], vcc
	s_cbranch_execz .LBB0_38
	s_mov_b32 s24, 1
	s_mov_b64 s[14:15], 0
	v_mov_b32_e32 v1, 0
	s_branch .LBB0_29

.LBB0_38:
	s_or_b64 exec, exec, s[10:11]
	s_waitcnt vmcnt(0)
	s_nop 0
	s_waitcnt vmcnt(0)
.LBB0_39:
	s_andn2_saveexec_b64 s[8:9], s[8:9]
	s_cbranch_execz .LBB0_59
	s_mov_b64 s[8:9], exec
	buffer_wbl2 sc1
	buffer_inv sc1
	s_waitcnt lgkmcnt(0)
	s_waitcnt vmcnt(0)
	v_mbcnt_lo_u32_b32 v2, s8, 0
	v_mbcnt_hi_u32_b32 v2, s9, v2
	v_cmp_eq_u32_e32 vcc, 0, v2
	s_and_saveexec_b64 s[10:11], vcc
	s_cbranch_execz .LBB0_42
	s_bcnt1_i32_b64 s8, s[8:9]
	v_mov_b32_e32 v3, 0x3000
	v_mov_b32_e32 v4, s8
	global_atomic_add v3, v3, v4, s[92:93] offset:1024 sc0

.LBB0_56:
	s_or_b64 exec, exec, s[8:9]
	s_mov_b64 s[8:9], exec
	v_mbcnt_lo_u32_b32 v1, s8, 0
	v_mbcnt_hi_u32_b32 v1, s9, v1
	v_cmp_eq_u32_e32 vcc, 0, v1
	s_waitcnt vmcnt(0)
	s_nop 0
	s_and_saveexec_b64 s[10:11], vcc
	s_cbranch_execz .LBB0_58
	s_bcnt1_i32_b64 s8, s[8:9]
	v_mov_b32_e32 v1, 0x2000
	v_mov_b32_e32 v2, s8
	global_atomic_add v1, v2, s[6:7] offset:1024

.LBB0_167:
	s_or_b64 exec, exec, s[8:9]
	v_cvt_f32_u32_e32 v5, v3
	s_waitcnt vmcnt(0)
	v_readfirstlane_b32 s6, v4
	v_sub_u32_e32 v4, 0, v3
	v_rcp_iflag_f32_e32 v5, v5
	v_add_u32_e32 v6, s6, v2
	v_mul_f32_e32 v5, 0x4f7ffffe, v5
	v_cvt_u32_f32_e32 v5, v5
	v_mul_lo_u32 v2, v4, v5
	v_mul_hi_u32 v2, v5, v2
	v_add_u32_e32 v2, v5, v2
	v_mul_hi_u32 v2, v6, v2
	v_mul_lo_u32 v4, v2, v3
	v_sub_u32_e32 v4, v6, v4
	v_add_u32_e32 v5, 1, v2
	v_sub_u32_e32 v7, v4, v3
	v_cmp_ge_u32_e32 vcc, v4, v3
	s_nop 1
	v_cndmask_b32_e32 v2, v2, v5, vcc
	v_cndmask_b32_e32 v4, v4, v7, vcc
	v_add_u32_e32 v5, 1, v2
	v_cmp_ge_u32_e32 vcc, v4, v3
	v_add_u32_e32 v4, 1, v6
	s_nop 0
	v_cndmask_b32_e32 v2, v2, v5, vcc
	v_mul_lo_u32 v5, v3, v2
	v_add_u32_e32 v3, v5, v3
	v_cmp_ne_u32_e32 vcc, v4, v3
	s_and_saveexec_b64 s[6:7], vcc
	s_xor_b64 s[6:7], exec, s[6:7]
	s_cbranch_execz .LBB0_181
	s_waitcnt lgkmcnt(0)
	buffer_inv sc1
	v_mov_b32_e32 v1, 0x2000
	global_load_dword v1, v1, s[2:3] offset:1024 sc1
	s_add_u32 s10, s2, 0x2400
	s_addc_u32 s11, s3, 0
	s_waitcnt vmcnt(0)
	v_cmp_eq_u32_e32 vcc, v1, v2
	s_and_saveexec_b64 s[8:9], vcc
	s_cbranch_execz .LBB0_180
	s_mov_b32 s22, 1
	s_mov_b64 s[12:13], 0
	v_mov_b32_e32 v1, 0
	s_branch .LBB0_171

.LBB0_180:
	s_or_b64 exec, exec, s[8:9]
	s_waitcnt vmcnt(0)
	s_nop 0
	s_waitcnt vmcnt(0)
.LBB0_181:
	s_andn2_saveexec_b64 s[6:7], s[6:7]
	s_cbranch_execz .LBB0_201
	s_mov_b64 s[6:7], exec
	buffer_wbl2 sc1
	buffer_inv sc1
	s_waitcnt lgkmcnt(0)
	s_waitcnt vmcnt(0)
	v_mbcnt_lo_u32_b32 v2, s6, 0
	v_mbcnt_hi_u32_b32 v2, s7, v2
	v_cmp_eq_u32_e32 vcc, 0, v2
	s_and_saveexec_b64 s[8:9], vcc
	s_cbranch_execz .LBB0_184
	s_bcnt1_i32_b64 s6, s[6:7]
	v_mov_b32_e32 v3, 0x3000
	v_mov_b32_e32 v4, s6
	global_atomic_add v3, v3, v4, s[92:93] offset:1024 sc0

.LBB0_198:
	s_or_b64 exec, exec, s[6:7]
	s_mov_b64 s[6:7], exec
	v_mbcnt_lo_u32_b32 v1, s6, 0
	v_mbcnt_hi_u32_b32 v1, s7, v1
	v_cmp_eq_u32_e32 vcc, 0, v1
	s_waitcnt vmcnt(0)
	s_nop 0
	s_and_saveexec_b64 s[8:9], vcc
	s_cbranch_execz .LBB0_200
	s_bcnt1_i32_b64 s6, s[6:7]
	v_mov_b32_e32 v1, 0x2000
	v_mov_b32_e32 v2, s6
	global_atomic_add v1, v2, s[2:3] offset:1024

.LBB0_230:
	s_or_b64 exec, exec, s[6:7]
	v_cvt_f32_u32_e32 v5, v3
	s_waitcnt vmcnt(0)
	v_readfirstlane_b32 s4, v4
	v_sub_u32_e32 v4, 0, v3
	v_rcp_iflag_f32_e32 v5, v5
	v_add_u32_e32 v6, s4, v2
	v_mul_f32_e32 v5, 0x4f7ffffe, v5
	v_cvt_u32_f32_e32 v5, v5
	v_mul_lo_u32 v2, v4, v5
	v_mul_hi_u32 v2, v5, v2
	v_add_u32_e32 v2, v5, v2
	v_mul_hi_u32 v2, v6, v2
	v_mul_lo_u32 v4, v2, v3
	v_sub_u32_e32 v4, v6, v4
	v_add_u32_e32 v5, 1, v2
	v_sub_u32_e32 v7, v4, v3
	v_cmp_ge_u32_e32 vcc, v4, v3
	s_nop 1
	v_cndmask_b32_e32 v2, v2, v5, vcc
	v_cndmask_b32_e32 v4, v4, v7, vcc
	v_add_u32_e32 v5, 1, v2
	v_cmp_ge_u32_e32 vcc, v4, v3
	v_add_u32_e32 v4, 1, v6
	s_nop 0
	v_cndmask_b32_e32 v2, v2, v5, vcc
	v_mul_lo_u32 v5, v3, v2
	v_add_u32_e32 v3, v5, v3
	v_cmp_ne_u32_e32 vcc, v4, v3
	s_and_saveexec_b64 s[4:5], vcc
	s_xor_b64 s[4:5], exec, s[4:5]
	s_cbranch_execz .LBB0_244
	s_waitcnt lgkmcnt(0)
	buffer_inv sc1
	v_mov_b32_e32 v1, 0x2000
	global_load_dword v1, v1, s[2:3] offset:1024 sc1
	s_add_u32 s8, s2, 0x2400
	s_addc_u32 s9, s3, 0
	s_waitcnt vmcnt(0)
	v_cmp_eq_u32_e32 vcc, v1, v2
	s_and_saveexec_b64 s[6:7], vcc
	s_cbranch_execz .LBB0_243
	s_mov_b32 s20, 1
	s_mov_b64 s[10:11], 0
	v_mov_b32_e32 v1, 0
	s_branch .LBB0_234

.LBB0_243:
	s_or_b64 exec, exec, s[6:7]
	s_waitcnt vmcnt(0)
	s_nop 0
	s_waitcnt vmcnt(0)
.LBB0_244:
	s_andn2_saveexec_b64 s[4:5], s[4:5]
	s_cbranch_execz .LBB0_264
	s_mov_b64 s[4:5], exec
	buffer_wbl2 sc1
	buffer_inv sc1
	s_waitcnt lgkmcnt(0)
	s_waitcnt vmcnt(0)
	v_mbcnt_lo_u32_b32 v2, s4, 0
	v_mbcnt_hi_u32_b32 v2, s5, v2
	v_cmp_eq_u32_e32 vcc, 0, v2
	s_and_saveexec_b64 s[6:7], vcc
	s_cbranch_execz .LBB0_247
	s_bcnt1_i32_b64 s4, s[4:5]
	v_mov_b32_e32 v3, 0x3000
	v_mov_b32_e32 v4, s4
	global_atomic_add v3, v3, v4, s[92:93] offset:1024 sc0

.LBB0_261:
	s_or_b64 exec, exec, s[4:5]
	s_mov_b64 s[4:5], exec
	v_mbcnt_lo_u32_b32 v1, s4, 0
	v_mbcnt_hi_u32_b32 v1, s5, v1
	v_cmp_eq_u32_e32 vcc, 0, v1
	s_waitcnt vmcnt(0)
	s_nop 0
	s_and_saveexec_b64 s[6:7], vcc
	s_cbranch_execz .LBB0_263
	s_bcnt1_i32_b64 s4, s[4:5]
	v_mov_b32_e32 v1, 0x2000
	v_mov_b32_e32 v2, s4
	global_atomic_add v1, v2, s[2:3] offset:1024

.LBB0_412:
	s_or_b64 exec, exec, s[8:9]
	v_cvt_f32_u32_e32 v5, v3
	s_waitcnt vmcnt(0)
	v_readfirstlane_b32 s6, v4
	v_sub_u32_e32 v4, 0, v3
	v_rcp_iflag_f32_e32 v5, v5
	v_add_u32_e32 v6, s6, v1
	v_mul_f32_e32 v5, 0x4f7ffffe, v5
	v_cvt_u32_f32_e32 v5, v5
	v_mul_lo_u32 v1, v4, v5
	v_mul_hi_u32 v1, v5, v1
	v_add_u32_e32 v1, v5, v1
	v_mul_hi_u32 v1, v6, v1
	v_mul_lo_u32 v4, v1, v3
	v_sub_u32_e32 v4, v6, v4
	v_add_u32_e32 v5, 1, v1
	v_cmp_ge_u32_e32 vcc, v4, v3
	s_nop 1
	v_cndmask_b32_e32 v1, v1, v5, vcc
	v_sub_u32_e32 v5, v4, v3
	v_cndmask_b32_e32 v4, v4, v5, vcc
	v_add_u32_e32 v5, 1, v1
	v_cmp_ge_u32_e32 vcc, v4, v3
	v_add_u32_e32 v4, 1, v6
	s_nop 0
	v_cndmask_b32_e32 v1, v1, v5, vcc
	v_mul_lo_u32 v5, v3, v1
	v_add_u32_e32 v3, v5, v3
	v_cmp_ne_u32_e32 vcc, v4, v3
	s_and_saveexec_b64 s[6:7], vcc
	s_xor_b64 s[6:7], exec, s[6:7]
	s_cbranch_execz .LBB0_426
	s_waitcnt lgkmcnt(0)
	buffer_inv sc1
	v_mov_b32_e32 v2, 0x2000
	global_load_dword v2, v2, s[4:5] offset:1024 sc1
	s_add_u32 s10, s4, 0x2400
	s_addc_u32 s11, s5, 0
	s_waitcnt vmcnt(0)
	v_cmp_eq_u32_e32 vcc, v2, v1
	s_and_saveexec_b64 s[8:9], vcc
	s_cbranch_execz .LBB0_425
	s_mov_b32 s22, 1
	s_mov_b64 s[12:13], 0
	v_mov_b32_e32 v2, 0
	s_branch .LBB0_416

.LBB0_426:
	s_andn2_saveexec_b64 s[6:7], s[6:7]
	s_cbranch_execz .LBB0_446
	s_mov_b64 s[6:7], exec
	buffer_wbl2 sc1
	buffer_inv sc1
	s_waitcnt lgkmcnt(0)
	s_waitcnt vmcnt(0)
	v_mbcnt_lo_u32_b32 v1, s6, 0
	v_mbcnt_hi_u32_b32 v1, s7, v1
	v_cmp_eq_u32_e32 vcc, 0, v1
	s_and_saveexec_b64 s[8:9], vcc
	s_cbranch_execz .LBB0_429
	s_bcnt1_i32_b64 s6, s[6:7]
	v_mov_b32_e32 v3, 0x3000
	v_mov_b32_e32 v4, s6
	global_atomic_add v3, v3, v4, s[92:93] offset:1024 sc0

.LBB0_443:
	s_or_b64 exec, exec, s[6:7]
	s_mov_b64 s[6:7], exec
	v_mbcnt_lo_u32_b32 v1, s6, 0
	v_mbcnt_hi_u32_b32 v1, s7, v1
	v_cmp_eq_u32_e32 vcc, 0, v1
	s_waitcnt vmcnt(0)
	s_nop 0
	s_and_saveexec_b64 s[8:9], vcc
	s_cbranch_execz .LBB0_445
	s_bcnt1_i32_b64 s6, s[6:7]
	v_mov_b32_e32 v1, 0x2000
	v_mov_b32_e32 v2, s6
	global_atomic_add v1, v2, s[4:5] offset:1024

.LBB0_476:
	s_or_b64 exec, exec, s[8:9]
	v_cvt_f32_u32_e32 v5, v3
	s_waitcnt vmcnt(0)
	v_readfirstlane_b32 s6, v4
	v_sub_u32_e32 v4, 0, v3
	v_rcp_iflag_f32_e32 v5, v5
	v_add_u32_e32 v6, s6, v2
	v_mul_f32_e32 v5, 0x4f7ffffe, v5
	v_cvt_u32_f32_e32 v5, v5
	v_mul_lo_u32 v2, v4, v5
	v_mul_hi_u32 v2, v5, v2
	v_add_u32_e32 v2, v5, v2
	v_mul_hi_u32 v2, v6, v2
	v_mul_lo_u32 v4, v2, v3
	v_sub_u32_e32 v4, v6, v4
	v_add_u32_e32 v5, 1, v2
	v_cmp_ge_u32_e32 vcc, v4, v3
	s_nop 1
	v_cndmask_b32_e32 v2, v2, v5, vcc
	v_sub_u32_e32 v5, v4, v3
	v_cndmask_b32_e32 v4, v4, v5, vcc
	v_add_u32_e32 v5, 1, v2
	v_cmp_ge_u32_e32 vcc, v4, v3
	v_add_u32_e32 v4, 1, v6
	s_nop 0
	v_cndmask_b32_e32 v2, v2, v5, vcc
	v_mul_lo_u32 v5, v3, v2
	v_add_u32_e32 v3, v5, v3
	v_cmp_ne_u32_e32 vcc, v4, v3
	s_and_saveexec_b64 s[6:7], vcc
	s_xor_b64 s[6:7], exec, s[6:7]
	s_cbranch_execz .LBB0_490
	s_waitcnt lgkmcnt(0)
	buffer_inv sc1
	v_mov_b32_e32 v1, 0x2000
	global_load_dword v1, v1, s[4:5] offset:1024 sc1
	s_add_u32 s10, s4, 0x2400
	s_addc_u32 s11, s5, 0
	s_waitcnt vmcnt(0)
	v_cmp_eq_u32_e32 vcc, v1, v2
	s_and_saveexec_b64 s[8:9], vcc
	s_cbranch_execz .LBB0_489
	s_mov_b32 s22, 1
	s_mov_b64 s[12:13], 0
	v_mov_b32_e32 v1, 0
	s_branch .LBB0_480

.LBB0_600:
	s_or_b64 exec, exec, s[6:7]
	v_cvt_f32_u32_e32 v5, v3
	s_waitcnt vmcnt(0)
	v_readfirstlane_b32 s4, v4
	v_sub_u32_e32 v4, 0, v3
	v_rcp_iflag_f32_e32 v5, v5
	v_add_u32_e32 v6, s4, v2
	v_mul_f32_e32 v5, 0x4f7ffffe, v5
	v_cvt_u32_f32_e32 v5, v5
	v_mul_lo_u32 v2, v4, v5
	v_mul_hi_u32 v2, v5, v2
	v_add_u32_e32 v2, v5, v2
	v_mul_hi_u32 v2, v6, v2
	v_mul_lo_u32 v4, v2, v3
	v_sub_u32_e32 v4, v6, v4
	v_add_u32_e32 v5, 1, v2
	v_cmp_ge_u32_e32 vcc, v4, v3
	s_nop 1
	v_cndmask_b32_e32 v2, v2, v5, vcc
	v_sub_u32_e32 v5, v4, v3
	v_cndmask_b32_e32 v4, v4, v5, vcc
	v_add_u32_e32 v5, 1, v2
	v_cmp_ge_u32_e32 vcc, v4, v3
	v_add_u32_e32 v4, 1, v6
	s_nop 0
	v_cndmask_b32_e32 v2, v2, v5, vcc
	v_mul_lo_u32 v5, v3, v2
	v_add_u32_e32 v3, v5, v3
	v_cmp_ne_u32_e32 vcc, v4, v3
	s_and_saveexec_b64 s[4:5], vcc
	s_xor_b64 s[4:5], exec, s[4:5]
	s_cbranch_execz .LBB0_614
	s_waitcnt lgkmcnt(0)
	buffer_inv sc1
	v_mov_b32_e32 v1, 0x2000
	global_load_dword v1, v1, s[2:3] offset:1024 sc1
	s_add_u32 s8, s2, 0x2400
	s_addc_u32 s9, s3, 0
	s_waitcnt vmcnt(0)
	v_cmp_eq_u32_e32 vcc, v1, v2
	s_and_saveexec_b64 s[6:7], vcc
	s_cbranch_execz .LBB0_613
	s_mov_b32 s22, 1
	s_mov_b64 s[10:11], 0
	v_mov_b32_e32 v1, 0
	s_branch .LBB0_604

.Lbd_normal_0:
	s_waitcnt lgkmcnt(0)
	buffer_inv sc1
	v_mov_b32_e32 v1, 0x2000
	global_load_dword v1, v1, s[4:5] offset:1024 sc1
	s_add_u32 s10, s4, 0x2400
	s_addc_u32 s11, s5, 0
	s_waitcnt vmcnt(0)
	v_cmp_eq_u32_e32 vcc, v1, v2
	s_and_saveexec_b64 s[8:9], vcc
	s_cbranch_execz .LBB0_679
	s_mov_b32 s22, 1
	s_mov_b64 s[12:13], 0
	v_mov_b32_e32 v1, 0
	s_branch .LBB0_670

.LBB0_860:
	s_or_b64 exec, exec, s[6:7]
	v_cvt_f32_u32_e32 v5, v3
	s_waitcnt vmcnt(0)
	v_readfirstlane_b32 s4, v4
	v_sub_u32_e32 v4, 0, v3
	v_rcp_iflag_f32_e32 v5, v5
	v_add_u32_e32 v6, s4, v2
	v_mul_f32_e32 v5, 0x4f7ffffe, v5
	v_cvt_u32_f32_e32 v5, v5
	v_mul_lo_u32 v2, v4, v5
	v_mul_hi_u32 v2, v5, v2
	v_add_u32_e32 v2, v5, v2
	v_mul_hi_u32 v2, v6, v2
	v_mul_lo_u32 v4, v2, v3
	v_sub_u32_e32 v4, v6, v4
	v_add_u32_e32 v5, 1, v2
	v_cmp_ge_u32_e32 vcc, v4, v3
	s_nop 1
	v_cndmask_b32_e32 v2, v2, v5, vcc
	v_sub_u32_e32 v5, v4, v3
	v_cndmask_b32_e32 v4, v4, v5, vcc
	v_add_u32_e32 v5, 1, v2
	v_cmp_ge_u32_e32 vcc, v4, v3
	v_add_u32_e32 v4, 1, v6
	s_nop 0
	v_cndmask_b32_e32 v2, v2, v5, vcc
	v_mul_lo_u32 v5, v3, v2
	v_add_u32_e32 v3, v5, v3
	v_cmp_ne_u32_e32 vcc, v4, v3
	s_and_saveexec_b64 s[4:5], vcc
	s_xor_b64 s[4:5], exec, s[4:5]
	s_cbranch_execz .LBB0_874
	s_waitcnt lgkmcnt(0)
	buffer_inv sc1
	v_mov_b32_e32 v1, 0x2000
	global_load_dword v1, v1, s[2:3] offset:1024 sc1
	s_add_u32 s8, s2, 0x2400
	s_addc_u32 s9, s3, 0
	s_waitcnt vmcnt(0)
	v_cmp_eq_u32_e32 vcc, v1, v2
	s_and_saveexec_b64 s[6:7], vcc
	s_cbranch_execz .LBB0_873
	s_mov_b32 s20, 1
	s_mov_b64 s[10:11], 0
	v_mov_b32_e32 v1, 0
	s_branch .LBB0_864

.LBB0_919:
	s_or_b64 exec, exec, s[8:9]
	v_cvt_f32_u32_e32 v5, v3
	s_waitcnt vmcnt(0)
	v_readfirstlane_b32 s4, v4
	v_sub_u32_e32 v4, 0, v3
	v_rcp_iflag_f32_e32 v5, v5
	v_add_u32_e32 v6, s4, v2
	v_mul_f32_e32 v5, 0x4f7ffffe, v5
	v_cvt_u32_f32_e32 v5, v5
	v_mul_lo_u32 v2, v4, v5
	v_mul_hi_u32 v2, v5, v2
	v_add_u32_e32 v2, v5, v2
	v_mul_hi_u32 v2, v6, v2
	v_mul_lo_u32 v4, v2, v3
	v_sub_u32_e32 v4, v6, v4
	v_add_u32_e32 v5, 1, v2
	v_cmp_ge_u32_e32 vcc, v4, v3
	s_nop 1
	v_cndmask_b32_e32 v2, v2, v5, vcc
	v_sub_u32_e32 v5, v4, v3
	v_cndmask_b32_e32 v4, v4, v5, vcc
	v_add_u32_e32 v5, 1, v2
	v_cmp_ge_u32_e32 vcc, v4, v3
	v_add_u32_e32 v4, 1, v6
	s_nop 0
	v_cndmask_b32_e32 v2, v2, v5, vcc
	v_mul_lo_u32 v5, v3, v2
	v_add_u32_e32 v3, v5, v3
	v_cmp_ne_u32_e32 vcc, v4, v3
	s_and_saveexec_b64 s[4:5], vcc
	s_xor_b64 s[4:5], exec, s[4:5]
	s_cbranch_execz .LBB0_933
	s_waitcnt lgkmcnt(0)
	buffer_inv sc1
	v_mov_b32_e32 v1, 0x2000
	global_load_dword v1, v1, s[2:3] offset:1024 sc1
	s_add_u32 s10, s2, 0x2400
	s_addc_u32 s11, s3, 0
	s_waitcnt vmcnt(0)
	v_cmp_eq_u32_e32 vcc, v1, v2
	s_and_saveexec_b64 s[8:9], vcc
	s_cbranch_execz .LBB0_932
	s_mov_b32 s22, 1
	s_mov_b64 s[12:13], 0
	v_mov_b32_e32 v1, 0
	s_branch .LBB0_923

.LBB0_933:
	s_andn2_saveexec_b64 s[4:5], s[4:5]
	s_cbranch_execz .LBB0_953
	s_mov_b64 s[4:5], exec
	buffer_wbl2 sc1
	buffer_inv sc1
	s_waitcnt lgkmcnt(0)
	s_waitcnt vmcnt(0)
	v_mbcnt_lo_u32_b32 v2, s4, 0
	v_mbcnt_hi_u32_b32 v2, s5, v2
	v_cmp_eq_u32_e32 vcc, 0, v2
	s_and_saveexec_b64 s[8:9], vcc
	s_cbranch_execz .LBB0_936
	s_bcnt1_i32_b64 s4, s[4:5]
	v_mov_b32_e32 v3, 0x3000
	v_mov_b32_e32 v4, s4
	global_atomic_add v3, v3, v4, s[92:93] offset:1024 sc0

.LBB0_950:
	s_or_b64 exec, exec, s[4:5]
	s_mov_b64 s[4:5], exec
	v_mbcnt_lo_u32_b32 v1, s4, 0
	v_mbcnt_hi_u32_b32 v1, s5, v1
	v_cmp_eq_u32_e32 vcc, 0, v1
	s_waitcnt vmcnt(0)
	s_nop 0
	s_and_saveexec_b64 s[8:9], vcc
	s_cbranch_execz .LBB0_952
	s_bcnt1_i32_b64 s4, s[4:5]
	v_mov_b32_e32 v1, 0x2000
	v_mov_b32_e32 v2, s4
	global_atomic_add v1, v2, s[2:3] offset:1024

.LBB0_1065:
	s_or_b64 exec, exec, s[8:9]
	v_cvt_f32_u32_e32 v5, v3
	s_waitcnt vmcnt(0)
	v_readfirstlane_b32 s6, v4
	v_sub_u32_e32 v4, 0, v3
	v_rcp_iflag_f32_e32 v5, v5
	v_add_u32_e32 v6, s6, v2
	v_mul_f32_e32 v5, 0x4f7ffffe, v5
	v_cvt_u32_f32_e32 v5, v5
	v_mul_lo_u32 v2, v4, v5
	v_mul_hi_u32 v2, v5, v2
	v_add_u32_e32 v2, v5, v2
	v_mul_hi_u32 v2, v6, v2
	v_mul_lo_u32 v4, v2, v3
	v_sub_u32_e32 v4, v6, v4
	v_add_u32_e32 v5, 1, v2
	v_cmp_ge_u32_e32 vcc, v4, v3
	s_nop 1
	v_cndmask_b32_e32 v2, v2, v5, vcc
	v_sub_u32_e32 v5, v4, v3
	v_cndmask_b32_e32 v4, v4, v5, vcc
	v_add_u32_e32 v5, 1, v2
	v_cmp_ge_u32_e32 vcc, v4, v3
	v_add_u32_e32 v4, 1, v6
	s_nop 0
	v_cndmask_b32_e32 v2, v2, v5, vcc
	v_mul_lo_u32 v5, v3, v2
	v_add_u32_e32 v3, v5, v3
	v_cmp_ne_u32_e32 vcc, v4, v3
	s_and_saveexec_b64 s[6:7], vcc
	s_xor_b64 s[6:7], exec, s[6:7]
	s_cbranch_execz .LBB0_1079
	s_waitcnt lgkmcnt(0)
	buffer_inv sc1
	v_mov_b32_e32 v1, 0x2000
	global_load_dword v1, v1, s[2:3] offset:1024 sc1
	s_add_u32 s10, s2, 0x2400
	s_addc_u32 s11, s3, 0
	s_waitcnt vmcnt(0)
	v_cmp_eq_u32_e32 vcc, v1, v2
	s_and_saveexec_b64 s[8:9], vcc
	s_cbranch_execz .LBB0_1078
	s_mov_b32 s22, 1
	s_mov_b64 s[12:13], 0
	v_mov_b32_e32 v1, 0
	s_branch .LBB0_1069

.Lbd_normal_1:
	s_waitcnt lgkmcnt(0)
	buffer_inv sc1
	v_mov_b32_e32 v1, 0x2000
	global_load_dword v1, v1, s[2:3] offset:1024 sc1
	s_add_u32 s8, s2, 0x2400
	s_addc_u32 s9, s3, 0
	s_waitcnt vmcnt(0)
	v_cmp_eq_u32_e32 vcc, v1, v2
	s_and_saveexec_b64 s[6:7], vcc
	s_cbranch_execz .LBB0_1268
	s_mov_b32 s20, 1
	s_mov_b64 s[10:11], 0
	v_mov_b32_e32 v1, 0
	s_branch .LBB0_1259
